# prompt attention task prologue: third-group q loads issued with the first group (one round trip less per task)
# speedup vs baseline: 1.0091x; 1.0091x over previous
; __device__ __forceinline__ void unpack8(u32x4 u, float* f) { f[0] = bflo(u.x); f[1] = bfhi(u.x); f[2] = bflo(u.y); f[3] = bfhi(u.y); f[4] = bflo(u.z); f[5] = bfhi(u.z); f[6] = bflo(u.w); f[7] = bfhi(u.w); }
; __device__ __forceinline__ u32x4 pack8(const float* f) { u32x4 o; o.x = pk2(f[0], f[1]); o.y = pk2(f[2], f[3]); o.z = pk2(f[4], f[5]); o.w = pk2(f[6], f[7]); return o; }
; __device__ __forceinline__ void attn_prompt_item(const Args& A, LAS unsigned char* lds, int tid, int lane, int wave, int b, int nb, int kvh) {
;     ...
;     for (int task = wave; task < 16; task += 8) {
;         const int g = task >> 2, tt = task & 3, hq = kvh * 4 + g;
;         const float sink = A.sinks[hq] * 1.4426950408889634f;
;         bf16x8 Qf[2][2];
; #pragma unroll
;         for (int mt = 0; mt < 2; ++mt)
; #pragma unroll
;             for (int ks = 0; ks < 2; ++ks) {
;                 const int tq = tt * 32 + mt * 16 + fr; const int pos = nb * 128 + tq; const size_t row = (size_t)b * SEQ + pos;
;                 const bf16_t* qp = Z + row * NZ + O_Q + hq * 64; const int d0 = ks * 32 + q4 * 8;
;                 float qf[8]; unpack8(*(const u32x4*)(qp + d0), qf);
;                 if (ks == 0 && q4 < 2) { float pf[8]; unpack8(*(const u32x4*)(qp + (d0 ^ 8)), pf);
; #pragma unroll
;                     for (int i = 0; i < 8; ++i) { const float c = ct[pos * 8 + i], s = st[pos * 8 + i]; qf[i] = q4 == 0 ? qf[i] * c - pf[i] * s : qf[i] * c + pf[i] * s; } }
; #pragma unroll
;                 for (int i = 0; i < 8; ++i) qf[i] *= 0.18033688011112042f;
;                 Qf[mt][ks] = __builtin_bit_cast(bf16x8, pack8(qf));
;             }
.LBB0_307:
	s_lshr_b32 s8, s65, 2
	s_add_i32 s42, s8, s59
	s_lshl_b64 s[8:9], s[42:43], 2
	s_add_u32 s8, s92, s8
	s_addc_u32 s9, s93, s9
	global_load_dword v28, v67, s[8:9]
	s_lshl_b32 s8, s42, 7
	s_mov_b32 s9, s43
	v_lshl_add_u64 v[2:3], v[94:95], 0, s[8:9]
	v_lshlrev_b32_e32 v66, 1, v90
	v_lshl_add_u64 v[0:1], v[2:3], 0, v[66:67]
	global_load_dwordx4 v[4:7], v[0:1], off
	global_load_dwordx4 v[240:243], v[0:1], off offset:64
	v_lshl_add_u64 v[244:245], v[100:101], 0, s[8:9]
	v_lshl_add_u64 v[244:245], v[244:245], 0, v[66:67]
	global_load_dwordx4 v[236:239], v[244:245], off
	s_waitcnt vmcnt(0)
	v_lshlrev_b32_e32 v12, 16, v4
	v_and_b32_e32 v13, 0xffff0000, v4
	v_lshlrev_b32_e32 v14, 16, v5
	v_and_b32_e32 v15, 0xffff0000, v5
	v_lshlrev_b32_e32 v16, 16, v6
	v_and_b32_e32 v17, 0xffff0000, v6
	v_lshlrev_b32_e32 v18, 16, v7
	v_and_b32_e32 v19, 0xffff0000, v7
	v_lshlrev_b32_e32 v4, 1, v64
	s_and_saveexec_b64 s[8:9], s[4:5]
	s_cbranch_execz .LBB0_309
	v_mov_b32_e32 v5, v67
	v_lshl_add_u64 v[2:3], v[2:3], 0, v[4:5]
	global_load_dwordx4 v[6:9], v[2:3], off
	global_load_dwordx4 v[20:23], v[98:99], off
	global_load_dwordx4 v[24:27], v[98:99], off offset:16
	global_load_dwordx4 v[30:33], v[96:97], off
	global_load_dwordx4 v[34:37], v[96:97], off offset:16
	s_waitcnt vmcnt(4)
	v_lshlrev_b32_e32 v2, 16, v6
	v_and_b32_e32 v3, 0xffff0000, v6
	v_lshlrev_b32_e32 v6, 16, v7
	v_and_b32_e32 v7, 0xffff0000, v7
	v_lshlrev_b32_e32 v10, 16, v8
	v_and_b32_e32 v11, 0xffff0000, v8
	v_lshlrev_b32_e32 v8, 16, v9
	v_and_b32_e32 v9, 0xffff0000, v9
	s_waitcnt vmcnt(3)
	v_pk_mul_f32 v[2:3], v[20:21], v[2:3]
	v_pk_mul_f32 v[6:7], v[22:23], v[6:7]
	s_waitcnt vmcnt(2)
	v_pk_mul_f32 v[10:11], v[24:25], v[10:11]
	v_pk_mul_f32 v[8:9], v[26:27], v[8:9]
	v_cndmask_b32_e64 v3, v3, -v3, s[30:31]
	v_cndmask_b32_e64 v2, v2, -v2, s[30:31]
	v_cndmask_b32_e64 v7, v7, -v7, s[30:31]
	v_cndmask_b32_e64 v6, v6, -v6, s[30:31]
	v_cndmask_b32_e64 v11, v11, -v11, s[30:31]
	v_cndmask_b32_e64 v10, v10, -v10, s[30:31]
	v_cndmask_b32_e64 v9, v9, -v9, s[30:31]
	v_cndmask_b32_e64 v8, v8, -v8, s[30:31]
	s_waitcnt vmcnt(1)
	v_pk_fma_f32 v[12:13], v[30:31], v[12:13], v[2:3]
	v_pk_fma_f32 v[14:15], v[32:33], v[14:15], v[6:7]
	s_waitcnt vmcnt(0)
	v_pk_fma_f32 v[16:17], v[34:35], v[16:17], v[10:11]
	v_pk_fma_f32 v[18:19], v[36:37], v[18:19], v[8:9]
.LBB0_309:
	s_or_b64 exec, exec, s[8:9]
	s_lshl_b32 s8, s42, 6
	s_lshl_b32 s42, s8, 1
	v_lshl_add_u64 v[26:27], v[100:101], 0, s[42:43]
	v_lshl_add_u64 v[22:23], v[26:27], 0, v[66:67]
	v_mov_b32_e32 v30, v236
	v_mov_b32_e32 v31, v237
	v_mov_b32_e32 v32, v238
	v_mov_b32_e32 v33, v239
	v_mov_b32_e32 v8, v240
	v_mov_b32_e32 v9, v241
	v_mov_b32_e32 v10, v242
	v_mov_b32_e32 v11, v243
	s_waitcnt vmcnt(1)
	v_lshlrev_b32_e32 v0, 16, v30
	v_and_b32_e32 v20, 0xffff0000, v30
	v_lshlrev_b32_e32 v6, 16, v31
	v_and_b32_e32 v7, 0xffff0000, v31
	v_lshlrev_b32_e32 v24, 16, v32
	v_and_b32_e32 v25, 0xffff0000, v32
	v_lshlrev_b32_e32 v2, 16, v33
	v_and_b32_e32 v3, 0xffff0000, v33
	s_and_saveexec_b64 s[8:9], s[6:7]
	s_xor_b64 s[8:9], exec, s[8:9]
	s_andn2_saveexec_b64 s[8:9], s[8:9]
	s_cbranch_execz .LBB0_313
	global_load_dwordx3 v[42:44], v[102:103], off
	v_mov_b32_e32 v5, v67
	v_lshl_add_u64 v[4:5], v[26:27], 0, v[4:5]
	global_load_dwordx4 v[30:33], v[4:5], off
	global_load_dword v1, v[104:105], off
	global_load_dwordx4 v[34:37], v[106:107], off
	global_load_dwordx3 v[46:48], v[106:107], off offset:16
	global_load_dwordx4 v[38:41], v[108:109], off
	global_load_dword v29, v[108:109], off offset:16
	v_mov_b32_e32 v5, v2
	v_mov_b32_e32 v4, v25
	v_mov_b32_e32 v27, v24
	v_mov_b32_e32 v21, v6
	v_mov_b32_e32 v26, v7
	s_waitcnt vmcnt(5)
	v_lshlrev_b32_e32 v2, 16, v30
	v_and_b32_e32 v24, 0xffff0000, v30
	v_mov_b32_e32 v6, v43
	v_and_b32_e32 v43, 0xffff0000, v33
	v_lshlrev_b32_e32 v25, 16, v31
	v_and_b32_e32 v30, 0xffff0000, v31
	v_lshlrev_b32_e32 v31, 16, v32
	v_and_b32_e32 v32, 0xffff0000, v32
	v_lshlrev_b32_e32 v33, 16, v33
	s_waitcnt vmcnt(4)
	v_mul_f32_e32 v1, v1, v2
	s_waitcnt vmcnt(3)
	v_pk_mul_f32 v[24:25], v[34:35], v[24:25]
	v_pk_mul_f32 v[30:31], v[36:37], v[30:31]
	s_waitcnt vmcnt(2)
	v_pk_mul_f32 v[32:33], v[46:47], v[32:33]
	v_mul_f32_e32 v34, v48, v43
	v_cndmask_b32_e64 v2, v1, -v1, s[30:31]
	v_mov_b32_e32 v7, v44
	v_cndmask_b32_e64 v25, v25, -v25, s[30:31]
	v_cndmask_b32_e64 v24, v24, -v24, s[30:31]
	v_cndmask_b32_e64 v31, v31, -v31, s[30:31]
	v_cndmask_b32_e64 v30, v30, -v30, s[30:31]
	v_cndmask_b32_e64 v33, v33, -v33, s[30:31]
	v_cndmask_b32_e64 v32, v32, -v32, s[30:31]
	v_cndmask_b32_e64 v34, v34, -v34, s[30:31]
	v_fmac_f32_e32 v2, v42, v0
	v_pk_fma_f32 v[20:21], v[6:7], v[20:21], v[24:25]
	s_waitcnt vmcnt(1)
	v_pk_fma_f32 v[24:25], v[38:39], v[26:27], v[30:31]
	v_pk_fma_f32 v[26:27], v[40:41], v[4:5], v[32:33]
	s_waitcnt vmcnt(0)
	v_fmac_f32_e32 v34, v29, v3
	v_mov_b64_e32 v[0:1], v[2:3]
	v_mov_b64_e32 v[2:3], v[4:5]
	v_mov_b64_e32 v[4:5], v[6:7]
	v_mov_b64_e32 v[6:7], v[8:9]
	v_mov_b32_e32 v6, v21
	v_mov_b32_e32 v7, v24
	v_mov_b32_e32 v24, v25
	v_mov_b32_e32 v25, v26
	v_mov_b32_e32 v2, v27
	v_mov_b32_e32 v3, v34
